# prep conv: v rows split 5/5/5/1 per group across waves 4..7 so the gates wave carries one row
# baseline (speedup 1.0000x reference)
.Lcvi_v_f:
	s_cmp_eq_u32 s88, 0xe0
	s_cbranch_scc1 .Lcvi_w7_f
	s_lshr_b32 s28, s88, 5
	v_lshrrev_b32_e32 v3, 4, v160
	s_sub_u32 s29, s28, 4
	s_mul_i32 s29, s29, 20
	v_mad_u32_u24 v4, v3, 5, s29
	s_movk_i32 s99, 0x400
	s_bfe_u32 s28, s98, 0x20006
	s_lshl_b32 s28, s28, 7
	s_add_u32 s99, s99, s28
	v_and_b32_e32 v2, 15, v160
	v_lshl_add_u32 v5, v2, 3, s99
	v_lshlrev_b32_e32 v16, 2, v5
	v_add_u32_e32 v24, 0x1800, v16
	v_add_u32_e32 v34, 0x3000, v16
	v_add_u32_e32 v42, 0x4800, v16
	s_lshr_b32 s28, s98, 8
	s_lshl_b32 s28, s28, 12
	s_lshl_b32 s29, s98, 6
	s_and_b32 s29, s29, 0xfc0
	s_or_b32 s28, s28, s29
	s_sub_u32 s28, s28, 3
	v_add_u32_e32 v3, s28, v4
	v_lshlrev_b32_e32 v5, 1, v5
	v_add_u32_e32 v5, 0x800, v5
	v_mad_i32_i24 v50, v3, s76, v5
	v_add_u32_e32 v54, 0x1800, v50
	v_add_u32_e32 v58, 0x3000, v50
	v_add_u32_e32 v62, 0x4800, v50
	v_add_u32_e32 v66, 0x6000, v50
	v_add_u32_e32 v70, 0x7800, v50
	v_add_u32_e32 v74, 0x9000, v50
	v_add_u32_e32 v78, 0xa800, v50
	v_max_i32_e32 v50, 0, v50
	v_max_i32_e32 v54, 0, v54
	v_max_i32_e32 v58, 0, v58
	global_load_dwordx4 v[20:23], v16, s[72:73] offset:16
	global_load_dwordx4 v[16:19], v16, s[72:73]
	global_load_dwordx4 v[30:33], v24, s[72:73] offset:16
	global_load_dwordx4 v[24:27], v24, s[72:73]
	global_load_dwordx4 v[38:41], v34, s[72:73] offset:16
	global_load_dwordx4 v[34:37], v34, s[72:73]
	global_load_dwordx4 v[46:49], v42, s[72:73] offset:16
	global_load_dwordx4 v[42:45], v42, s[72:73]
	global_load_dwordx4 v[50:53], v50, s[70:71]
	global_load_dwordx4 v[54:57], v54, s[70:71]
	global_load_dwordx4 v[58:61], v58, s[70:71]
	global_load_dwordx4 v[62:65], v62, s[70:71]
	global_load_dwordx4 v[66:69], v66, s[70:71]
	global_load_dwordx4 v[70:73], v70, s[70:71]
	global_load_dwordx4 v[74:77], v74, s[70:71]
	global_load_dwordx4 v[78:81], v78, s[70:71]
	s_branch .Lcvi_done_f
.Lcvi_w7_f:
	s_lshr_b32 s28, s88, 5
	v_lshrrev_b32_e32 v3, 4, v160
	v_add_u32_e32 v4, 60, v3
	s_movk_i32 s99, 0x400
	s_bfe_u32 s28, s98, 0x20006
	s_lshl_b32 s28, s28, 7
	s_add_u32 s99, s99, s28
	v_and_b32_e32 v2, 15, v160
	v_lshl_add_u32 v5, v2, 3, s99
	v_lshlrev_b32_e32 v16, 2, v5
	v_add_u32_e32 v24, 0x1800, v16
	v_add_u32_e32 v34, 0x3000, v16
	v_add_u32_e32 v42, 0x4800, v16
	s_lshr_b32 s28, s98, 8
	s_lshl_b32 s28, s28, 12
	s_lshl_b32 s29, s98, 6
	s_and_b32 s29, s29, 0xfc0
	s_or_b32 s28, s28, s29
	s_sub_u32 s28, s28, 3
	v_add_u32_e32 v3, s28, v4
	v_lshlrev_b32_e32 v5, 1, v5
	v_add_u32_e32 v5, 0x800, v5
	v_mad_i32_i24 v50, v3, s76, v5
	v_add_u32_e32 v54, 0x1800, v50
	v_add_u32_e32 v58, 0x3000, v50
	v_add_u32_e32 v62, 0x4800, v50
	v_max_i32_e32 v50, 0, v50
	v_max_i32_e32 v54, 0, v54
	v_max_i32_e32 v58, 0, v58
	global_load_dwordx4 v[20:23], v16, s[72:73] offset:16
	global_load_dwordx4 v[16:19], v16, s[72:73]
	global_load_dwordx4 v[30:33], v24, s[72:73] offset:16
	global_load_dwordx4 v[24:27], v24, s[72:73]
	global_load_dwordx4 v[38:41], v34, s[72:73] offset:16
	global_load_dwordx4 v[34:37], v34, s[72:73]
	global_load_dwordx4 v[46:49], v42, s[72:73] offset:16
	global_load_dwordx4 v[42:45], v42, s[72:73]
	global_load_dwordx4 v[50:53], v50, s[70:71]
	global_load_dwordx4 v[54:57], v54, s[70:71]
	global_load_dwordx4 v[58:61], v58, s[70:71]
	global_load_dwordx4 v[62:65], v62, s[70:71]
	s_add_u32 s28, s28, 3
	v_add_u32_e32 v2, s28, v160
	s_bfe_u32 s99, s98, 0x20006
	s_lshl_b32 s28, s99, 2
	v_lshlrev_b32_e32 v2, 5, v2
	v_add_u32_e32 v2, s28, v2
	v_readlane_b32 s28, v254, 56
	v_readlane_b32 s29, v254, 57
	s_nop 4
	global_load_dword v92, v2, s[28:29]
	global_load_dword v93, v2, s[28:29] offset:16
	v_readlane_b32 s28, v254, 60
	s_nop 4
	s_add_u32 s99, s99, s28
	s_lshl_b32 s99, s99, 2
	v_mov_b32_e32 v3, s99
	v_readlane_b32 s28, v253, 50
	v_readlane_b32 s29, v253, 51
	s_nop 4
	global_load_dword v94, v3, s[28:29]
	v_readlane_b32 s28, v253, 48
	v_readlane_b32 s29, v253, 49
	s_nop 4
	global_load_dword v95, v3, s[28:29]

.Lcv_vwaves:
	s_cmp_eq_u32 s88, 0xe0
	s_cbranch_scc1 .Lcv_w7
	s_lshr_b32 s28, s88, 5
	v_lshrrev_b32_e32 v181, 4, v160
	s_sub_u32 s29, s28, 4
	s_mul_i32 s29, s29, 20
	v_mad_u32_u24 v180, v181, 5, s29
	s_mov_b32 s55, 2
	v_and_b32_e32 v128, 15, v160
	s_mul_i32 s28, s55, 0x8400
	v_lshlrev_b32_e32 v178, 9, v180
	v_lshl_add_u32 v178, v180, 4, v178
	v_lshl_add_u32 v178, v128, 5, v178
	v_add3_u32 v178, v178, v234, s28
	s_waitcnt vmcnt(11)
	s_cmp_lg_u32 s37, 0
	s_cbranch_scc1 .Lcv_nz_b
	v_cmp_eq_u32_e32 vcc, 0, v180
	s_nop 1
	v_cndmask_b32_e64 v50, v50, 0, vcc
	v_cndmask_b32_e64 v51, v51, 0, vcc
	v_cndmask_b32_e64 v52, v52, 0, vcc
	v_cndmask_b32_e64 v53, v53, 0, vcc
	v_cndmask_b32_e64 v54, v54, 0, vcc
	v_cndmask_b32_e64 v55, v55, 0, vcc
	v_cndmask_b32_e64 v56, v56, 0, vcc
	v_cndmask_b32_e64 v57, v57, 0, vcc
	v_cndmask_b32_e64 v58, v58, 0, vcc
	v_cndmask_b32_e64 v59, v59, 0, vcc
	v_cndmask_b32_e64 v60, v60, 0, vcc
	v_cndmask_b32_e64 v61, v61, 0, vcc
.Lcv_nz_b:
	v_lshlrev_b32_e32 v2, 16, v50
	v_and_b32_e32 v3, 0xffff0000, v50
	v_lshlrev_b32_e32 v4, 16, v51
	v_and_b32_e32 v5, 0xffff0000, v51
	v_lshlrev_b32_e32 v6, 16, v52
	v_and_b32_e32 v7, 0xffff0000, v52
	v_lshlrev_b32_e32 v8, 16, v53
	v_and_b32_e32 v9, 0xffff0000, v53
	v_lshlrev_b32_e32 v10, 16, v54
	v_and_b32_e32 v11, 0xffff0000, v54
	v_lshlrev_b32_e32 v12, 16, v55
	v_and_b32_e32 v13, 0xffff0000, v55
	v_lshlrev_b32_e32 v14, 16, v56
	v_and_b32_e32 v15, 0xffff0000, v56
	v_lshlrev_b32_e32 v100, 16, v57
	v_and_b32_e32 v101, 0xffff0000, v57
	v_lshlrev_b32_e32 v102, 16, v58
	v_and_b32_e32 v103, 0xffff0000, v58
	v_lshlrev_b32_e32 v104, 16, v59
	v_and_b32_e32 v105, 0xffff0000, v59
	v_lshlrev_b32_e32 v106, 16, v60
	v_and_b32_e32 v107, 0xffff0000, v60
	v_lshlrev_b32_e32 v108, 16, v61
	v_and_b32_e32 v109, 0xffff0000, v61
	s_waitcnt vmcnt(10)
	v_lshlrev_b32_e32 v110, 16, v62
	v_and_b32_e32 v111, 0xffff0000, v62
	v_lshlrev_b32_e32 v112, 16, v63
	v_and_b32_e32 v113, 0xffff0000, v63
	v_lshlrev_b32_e32 v114, 16, v64
	v_and_b32_e32 v115, 0xffff0000, v64
	v_lshlrev_b32_e32 v116, 16, v65
	v_and_b32_e32 v117, 0xffff0000, v65
	v_pk_mul_f32 v[124:125], v[16:17], v[2:3]
	v_pk_mul_f32 v[126:127], v[18:19], v[4:5]
	v_pk_mul_f32 v[118:119], v[20:21], v[6:7]
	v_pk_mul_f32 v[120:121], v[22:23], v[8:9]
	v_pk_fma_f32 v[124:125], v[24:25], v[10:11], v[124:125]
	v_pk_fma_f32 v[126:127], v[26:27], v[12:13], v[126:127]
	v_pk_fma_f32 v[118:119], v[30:31], v[14:15], v[118:119]
	v_pk_fma_f32 v[120:121], v[32:33], v[100:101], v[120:121]
	v_pk_fma_f32 v[124:125], v[34:35], v[102:103], v[124:125]
	v_pk_fma_f32 v[126:127], v[36:37], v[104:105], v[126:127]
	v_pk_fma_f32 v[118:119], v[38:39], v[106:107], v[118:119]
	v_pk_fma_f32 v[120:121], v[40:41], v[108:109], v[120:121]
	v_pk_fma_f32 v[124:125], v[42:43], v[110:111], v[124:125]
	v_pk_fma_f32 v[126:127], v[44:45], v[112:113], v[126:127]
	v_pk_fma_f32 v[118:119], v[46:47], v[114:115], v[118:119]
	v_pk_fma_f32 v[120:121], v[48:49], v[116:117], v[120:121]
	v_mul_f32_e32 v2, 0xbfb8aa3b, v124
	v_mul_f32_e32 v3, 0xbfb8aa3b, v125
	v_mul_f32_e32 v4, 0xbfb8aa3b, v126
	v_mul_f32_e32 v5, 0xbfb8aa3b, v127
	v_mul_f32_e32 v6, 0xbfb8aa3b, v118
	v_mul_f32_e32 v7, 0xbfb8aa3b, v119
	v_mul_f32_e32 v8, 0xbfb8aa3b, v120
	v_mul_f32_e32 v9, 0xbfb8aa3b, v121
	v_exp_f32_e32 v2, v2
	v_exp_f32_e32 v3, v3
	v_exp_f32_e32 v4, v4
	v_exp_f32_e32 v5, v5
	v_exp_f32_e32 v6, v6
	v_exp_f32_e32 v7, v7
	v_exp_f32_e32 v8, v8
	v_exp_f32_e32 v9, v9
	v_add_f32_e32 v2, 1.0, v2
	v_add_f32_e32 v3, 1.0, v3
	v_add_f32_e32 v4, 1.0, v4
	v_add_f32_e32 v5, 1.0, v5
	v_add_f32_e32 v6, 1.0, v6
	v_add_f32_e32 v7, 1.0, v7
	v_add_f32_e32 v8, 1.0, v8
	v_add_f32_e32 v9, 1.0, v9
	v_rcp_f32_e32 v2, v2
	v_rcp_f32_e32 v3, v3
	v_rcp_f32_e32 v4, v4
	v_rcp_f32_e32 v5, v5
	v_rcp_f32_e32 v6, v6
	v_rcp_f32_e32 v7, v7
	v_rcp_f32_e32 v8, v8
	v_rcp_f32_e32 v9, v9
	v_pk_mul_f32 v[124:125], v[124:125], v[2:3]
	v_pk_mul_f32 v[126:127], v[126:127], v[4:5]
	v_pk_mul_f32 v[118:119], v[118:119], v[6:7]
	v_pk_mul_f32 v[120:121], v[120:121], v[8:9]
	ds_write_b128 v178, v[124:127] offset:0
	ds_write_b128 v178, v[118:121] offset:16
	s_waitcnt vmcnt(9)
	v_lshlrev_b32_e32 v2, 16, v66
	v_and_b32_e32 v3, 0xffff0000, v66
	v_lshlrev_b32_e32 v4, 16, v67
	v_and_b32_e32 v5, 0xffff0000, v67
	v_lshlrev_b32_e32 v6, 16, v68
	v_and_b32_e32 v7, 0xffff0000, v68
	v_lshlrev_b32_e32 v8, 16, v69
	v_and_b32_e32 v9, 0xffff0000, v69
	v_pk_mul_f32 v[124:125], v[16:17], v[10:11]
	v_pk_mul_f32 v[126:127], v[18:19], v[12:13]
	v_pk_mul_f32 v[118:119], v[20:21], v[14:15]
	v_pk_mul_f32 v[120:121], v[22:23], v[100:101]
	v_pk_fma_f32 v[124:125], v[24:25], v[102:103], v[124:125]
	v_pk_fma_f32 v[126:127], v[26:27], v[104:105], v[126:127]
	v_pk_fma_f32 v[118:119], v[30:31], v[106:107], v[118:119]
	v_pk_fma_f32 v[120:121], v[32:33], v[108:109], v[120:121]
	v_pk_fma_f32 v[124:125], v[34:35], v[110:111], v[124:125]
	v_pk_fma_f32 v[126:127], v[36:37], v[112:113], v[126:127]
	v_pk_fma_f32 v[118:119], v[38:39], v[114:115], v[118:119]
	v_pk_fma_f32 v[120:121], v[40:41], v[116:117], v[120:121]
	v_pk_fma_f32 v[124:125], v[42:43], v[2:3], v[124:125]
	v_pk_fma_f32 v[126:127], v[44:45], v[4:5], v[126:127]
	v_pk_fma_f32 v[118:119], v[46:47], v[6:7], v[118:119]
	v_pk_fma_f32 v[120:121], v[48:49], v[8:9], v[120:121]
	v_mul_f32_e32 v10, 0xbfb8aa3b, v124
	v_mul_f32_e32 v11, 0xbfb8aa3b, v125
	v_mul_f32_e32 v12, 0xbfb8aa3b, v126
	v_mul_f32_e32 v13, 0xbfb8aa3b, v127
	v_mul_f32_e32 v14, 0xbfb8aa3b, v118
	v_mul_f32_e32 v15, 0xbfb8aa3b, v119
	v_mul_f32_e32 v100, 0xbfb8aa3b, v120
	v_mul_f32_e32 v101, 0xbfb8aa3b, v121
	v_exp_f32_e32 v10, v10
	v_exp_f32_e32 v11, v11
	v_exp_f32_e32 v12, v12
	v_exp_f32_e32 v13, v13
	v_exp_f32_e32 v14, v14
	v_exp_f32_e32 v15, v15
	v_exp_f32_e32 v100, v100
	v_exp_f32_e32 v101, v101
	v_add_f32_e32 v10, 1.0, v10
	v_add_f32_e32 v11, 1.0, v11
	v_add_f32_e32 v12, 1.0, v12
	v_add_f32_e32 v13, 1.0, v13
	v_add_f32_e32 v14, 1.0, v14
	v_add_f32_e32 v15, 1.0, v15
	v_add_f32_e32 v100, 1.0, v100
	v_add_f32_e32 v101, 1.0, v101
	v_rcp_f32_e32 v10, v10
	v_rcp_f32_e32 v11, v11
	v_rcp_f32_e32 v12, v12
	v_rcp_f32_e32 v13, v13
	v_rcp_f32_e32 v14, v14
	v_rcp_f32_e32 v15, v15
	v_rcp_f32_e32 v100, v100
	v_rcp_f32_e32 v101, v101
	v_pk_mul_f32 v[124:125], v[124:125], v[10:11]
	v_pk_mul_f32 v[126:127], v[126:127], v[12:13]
	v_pk_mul_f32 v[118:119], v[118:119], v[14:15]
	v_pk_mul_f32 v[120:121], v[120:121], v[100:101]
	ds_write_b128 v178, v[124:127] offset:528
	ds_write_b128 v178, v[118:121] offset:544
	s_waitcnt vmcnt(8)
	v_lshlrev_b32_e32 v10, 16, v70
	v_and_b32_e32 v11, 0xffff0000, v70
	v_lshlrev_b32_e32 v12, 16, v71
	v_and_b32_e32 v13, 0xffff0000, v71
	v_lshlrev_b32_e32 v14, 16, v72
	v_and_b32_e32 v15, 0xffff0000, v72
	v_lshlrev_b32_e32 v100, 16, v73
	v_and_b32_e32 v101, 0xffff0000, v73
	v_pk_mul_f32 v[124:125], v[16:17], v[102:103]
	v_pk_mul_f32 v[126:127], v[18:19], v[104:105]
	v_pk_mul_f32 v[118:119], v[20:21], v[106:107]
	v_pk_mul_f32 v[120:121], v[22:23], v[108:109]
	v_pk_fma_f32 v[124:125], v[24:25], v[110:111], v[124:125]
	v_pk_fma_f32 v[126:127], v[26:27], v[112:113], v[126:127]
	v_pk_fma_f32 v[118:119], v[30:31], v[114:115], v[118:119]
	v_pk_fma_f32 v[120:121], v[32:33], v[116:117], v[120:121]
	v_pk_fma_f32 v[124:125], v[34:35], v[2:3], v[124:125]
	v_pk_fma_f32 v[126:127], v[36:37], v[4:5], v[126:127]
	v_pk_fma_f32 v[118:119], v[38:39], v[6:7], v[118:119]
	v_pk_fma_f32 v[120:121], v[40:41], v[8:9], v[120:121]
	v_pk_fma_f32 v[124:125], v[42:43], v[10:11], v[124:125]
	v_pk_fma_f32 v[126:127], v[44:45], v[12:13], v[126:127]
	v_pk_fma_f32 v[118:119], v[46:47], v[14:15], v[118:119]
	v_pk_fma_f32 v[120:121], v[48:49], v[100:101], v[120:121]
	v_mul_f32_e32 v102, 0xbfb8aa3b, v124
	v_mul_f32_e32 v103, 0xbfb8aa3b, v125
	v_mul_f32_e32 v104, 0xbfb8aa3b, v126
	v_mul_f32_e32 v105, 0xbfb8aa3b, v127
	v_mul_f32_e32 v106, 0xbfb8aa3b, v118
	v_mul_f32_e32 v107, 0xbfb8aa3b, v119
	v_mul_f32_e32 v108, 0xbfb8aa3b, v120
	v_mul_f32_e32 v109, 0xbfb8aa3b, v121
	v_exp_f32_e32 v102, v102
	v_exp_f32_e32 v103, v103
	v_exp_f32_e32 v104, v104
	v_exp_f32_e32 v105, v105
	v_exp_f32_e32 v106, v106
	v_exp_f32_e32 v107, v107
	v_exp_f32_e32 v108, v108
	v_exp_f32_e32 v109, v109
	v_add_f32_e32 v102, 1.0, v102
	v_add_f32_e32 v103, 1.0, v103
	v_add_f32_e32 v104, 1.0, v104
	v_add_f32_e32 v105, 1.0, v105
	v_add_f32_e32 v106, 1.0, v106
	v_add_f32_e32 v107, 1.0, v107
	v_add_f32_e32 v108, 1.0, v108
	v_add_f32_e32 v109, 1.0, v109
	v_rcp_f32_e32 v102, v102
	v_rcp_f32_e32 v103, v103
	v_rcp_f32_e32 v104, v104
	v_rcp_f32_e32 v105, v105
	v_rcp_f32_e32 v106, v106
	v_rcp_f32_e32 v107, v107
	v_rcp_f32_e32 v108, v108
	v_rcp_f32_e32 v109, v109
	v_pk_mul_f32 v[124:125], v[124:125], v[102:103]
	v_pk_mul_f32 v[126:127], v[126:127], v[104:105]
	v_pk_mul_f32 v[118:119], v[118:119], v[106:107]
	v_pk_mul_f32 v[120:121], v[120:121], v[108:109]
	ds_write_b128 v178, v[124:127] offset:1056
	ds_write_b128 v178, v[118:121] offset:1072
	s_waitcnt vmcnt(7)
	v_lshlrev_b32_e32 v102, 16, v74
	v_and_b32_e32 v103, 0xffff0000, v74
	v_lshlrev_b32_e32 v104, 16, v75
	v_and_b32_e32 v105, 0xffff0000, v75
	v_lshlrev_b32_e32 v106, 16, v76
	v_and_b32_e32 v107, 0xffff0000, v76
	v_lshlrev_b32_e32 v108, 16, v77
	v_and_b32_e32 v109, 0xffff0000, v77
	v_pk_mul_f32 v[124:125], v[16:17], v[110:111]
	v_pk_mul_f32 v[126:127], v[18:19], v[112:113]
	v_pk_mul_f32 v[118:119], v[20:21], v[114:115]
	v_pk_mul_f32 v[120:121], v[22:23], v[116:117]
	v_pk_fma_f32 v[124:125], v[24:25], v[2:3], v[124:125]
	v_pk_fma_f32 v[126:127], v[26:27], v[4:5], v[126:127]
	v_pk_fma_f32 v[118:119], v[30:31], v[6:7], v[118:119]
	v_pk_fma_f32 v[120:121], v[32:33], v[8:9], v[120:121]
	v_pk_fma_f32 v[124:125], v[34:35], v[10:11], v[124:125]
	v_pk_fma_f32 v[126:127], v[36:37], v[12:13], v[126:127]
	v_pk_fma_f32 v[118:119], v[38:39], v[14:15], v[118:119]
	v_pk_fma_f32 v[120:121], v[40:41], v[100:101], v[120:121]
	v_pk_fma_f32 v[124:125], v[42:43], v[102:103], v[124:125]
	v_pk_fma_f32 v[126:127], v[44:45], v[104:105], v[126:127]
	v_pk_fma_f32 v[118:119], v[46:47], v[106:107], v[118:119]
	v_pk_fma_f32 v[120:121], v[48:49], v[108:109], v[120:121]
	v_mul_f32_e32 v110, 0xbfb8aa3b, v124
	v_mul_f32_e32 v111, 0xbfb8aa3b, v125
	v_mul_f32_e32 v112, 0xbfb8aa3b, v126
	v_mul_f32_e32 v113, 0xbfb8aa3b, v127
	v_mul_f32_e32 v114, 0xbfb8aa3b, v118
	v_mul_f32_e32 v115, 0xbfb8aa3b, v119
	v_mul_f32_e32 v116, 0xbfb8aa3b, v120
	v_mul_f32_e32 v117, 0xbfb8aa3b, v121
	v_exp_f32_e32 v110, v110
	v_exp_f32_e32 v111, v111
	v_exp_f32_e32 v112, v112
	v_exp_f32_e32 v113, v113
	v_exp_f32_e32 v114, v114
	v_exp_f32_e32 v115, v115
	v_exp_f32_e32 v116, v116
	v_exp_f32_e32 v117, v117
	v_add_f32_e32 v110, 1.0, v110
	v_add_f32_e32 v111, 1.0, v111
	v_add_f32_e32 v112, 1.0, v112
	v_add_f32_e32 v113, 1.0, v113
	v_add_f32_e32 v114, 1.0, v114
	v_add_f32_e32 v115, 1.0, v115
	v_add_f32_e32 v116, 1.0, v116
	v_add_f32_e32 v117, 1.0, v117
	v_rcp_f32_e32 v110, v110
	v_rcp_f32_e32 v111, v111
	v_rcp_f32_e32 v112, v112
	v_rcp_f32_e32 v113, v113
	v_rcp_f32_e32 v114, v114
	v_rcp_f32_e32 v115, v115
	v_rcp_f32_e32 v116, v116
	v_rcp_f32_e32 v117, v117
	v_pk_mul_f32 v[124:125], v[124:125], v[110:111]
	v_pk_mul_f32 v[126:127], v[126:127], v[112:113]
	v_pk_mul_f32 v[118:119], v[118:119], v[114:115]
	v_pk_mul_f32 v[120:121], v[120:121], v[116:117]
	ds_write_b128 v178, v[124:127] offset:1584
	ds_write_b128 v178, v[118:121] offset:1600
	s_waitcnt vmcnt(6)
	v_lshlrev_b32_e32 v110, 16, v78
	v_and_b32_e32 v111, 0xffff0000, v78
	v_lshlrev_b32_e32 v112, 16, v79
	v_and_b32_e32 v113, 0xffff0000, v79
	v_lshlrev_b32_e32 v114, 16, v80
	v_and_b32_e32 v115, 0xffff0000, v80
	v_lshlrev_b32_e32 v116, 16, v81
	v_and_b32_e32 v117, 0xffff0000, v81
	v_pk_mul_f32 v[124:125], v[16:17], v[2:3]
	v_pk_mul_f32 v[126:127], v[18:19], v[4:5]
	v_pk_mul_f32 v[118:119], v[20:21], v[6:7]
	v_pk_mul_f32 v[120:121], v[22:23], v[8:9]
	v_pk_fma_f32 v[124:125], v[24:25], v[10:11], v[124:125]
	v_pk_fma_f32 v[126:127], v[26:27], v[12:13], v[126:127]
	v_pk_fma_f32 v[118:119], v[30:31], v[14:15], v[118:119]
	v_pk_fma_f32 v[120:121], v[32:33], v[100:101], v[120:121]
	v_pk_fma_f32 v[124:125], v[34:35], v[102:103], v[124:125]
	v_pk_fma_f32 v[126:127], v[36:37], v[104:105], v[126:127]
	v_pk_fma_f32 v[118:119], v[38:39], v[106:107], v[118:119]
	v_pk_fma_f32 v[120:121], v[40:41], v[108:109], v[120:121]
	v_pk_fma_f32 v[124:125], v[42:43], v[110:111], v[124:125]
	v_pk_fma_f32 v[126:127], v[44:45], v[112:113], v[126:127]
	v_pk_fma_f32 v[118:119], v[46:47], v[114:115], v[118:119]
	v_pk_fma_f32 v[120:121], v[48:49], v[116:117], v[120:121]
	v_mul_f32_e32 v2, 0xbfb8aa3b, v124
	v_mul_f32_e32 v3, 0xbfb8aa3b, v125
	v_mul_f32_e32 v4, 0xbfb8aa3b, v126
	v_mul_f32_e32 v5, 0xbfb8aa3b, v127
	v_mul_f32_e32 v6, 0xbfb8aa3b, v118
	v_mul_f32_e32 v7, 0xbfb8aa3b, v119
	v_mul_f32_e32 v8, 0xbfb8aa3b, v120
	v_mul_f32_e32 v9, 0xbfb8aa3b, v121
	v_exp_f32_e32 v2, v2
	v_exp_f32_e32 v3, v3
	v_exp_f32_e32 v4, v4
	v_exp_f32_e32 v5, v5
	v_exp_f32_e32 v6, v6
	v_exp_f32_e32 v7, v7
	v_exp_f32_e32 v8, v8
	v_exp_f32_e32 v9, v9
	v_add_f32_e32 v2, 1.0, v2
	v_add_f32_e32 v3, 1.0, v3
	v_add_f32_e32 v4, 1.0, v4
	v_add_f32_e32 v5, 1.0, v5
	v_add_f32_e32 v6, 1.0, v6
	v_add_f32_e32 v7, 1.0, v7
	v_add_f32_e32 v8, 1.0, v8
	v_add_f32_e32 v9, 1.0, v9
	v_rcp_f32_e32 v2, v2
	v_rcp_f32_e32 v3, v3
	v_rcp_f32_e32 v4, v4
	v_rcp_f32_e32 v5, v5
	v_rcp_f32_e32 v6, v6
	v_rcp_f32_e32 v7, v7
	v_rcp_f32_e32 v8, v8
	v_rcp_f32_e32 v9, v9
	v_pk_mul_f32 v[124:125], v[124:125], v[2:3]
	v_pk_mul_f32 v[126:127], v[126:127], v[4:5]
	v_pk_mul_f32 v[118:119], v[118:119], v[6:7]
	v_pk_mul_f32 v[120:121], v[120:121], v[8:9]
	ds_write_b128 v178, v[124:127] offset:2112
	ds_write_b128 v178, v[118:121] offset:2128
	s_branch .Lcv_done
.Lcv_w7:
	s_lshr_b32 s28, s88, 5
	v_lshrrev_b32_e32 v181, 4, v160
	v_add_u32_e32 v180, 60, v181
	s_mov_b32 s55, 2
	v_and_b32_e32 v128, 15, v160
	s_mul_i32 s28, s55, 0x8400
	v_lshlrev_b32_e32 v178, 9, v180
	v_lshl_add_u32 v178, v180, 4, v178
	v_lshl_add_u32 v178, v128, 5, v178
	v_add3_u32 v178, v178, v234, s28
	s_waitcnt vmcnt(7)
	s_cmp_lg_u32 s37, 0
	s_cbranch_scc1 .Lcv_nz_c
	v_cmp_eq_u32_e32 vcc, 0, v180
	s_nop 1
	v_cndmask_b32_e64 v50, v50, 0, vcc
	v_cndmask_b32_e64 v51, v51, 0, vcc
	v_cndmask_b32_e64 v52, v52, 0, vcc
	v_cndmask_b32_e64 v53, v53, 0, vcc
	v_cndmask_b32_e64 v54, v54, 0, vcc
	v_cndmask_b32_e64 v55, v55, 0, vcc
	v_cndmask_b32_e64 v56, v56, 0, vcc
	v_cndmask_b32_e64 v57, v57, 0, vcc
	v_cndmask_b32_e64 v58, v58, 0, vcc
	v_cndmask_b32_e64 v59, v59, 0, vcc
	v_cndmask_b32_e64 v60, v60, 0, vcc
	v_cndmask_b32_e64 v61, v61, 0, vcc
.Lcv_nz_c:
	v_lshlrev_b32_e32 v2, 16, v50
	v_and_b32_e32 v3, 0xffff0000, v50
	v_lshlrev_b32_e32 v4, 16, v51
	v_and_b32_e32 v5, 0xffff0000, v51
	v_lshlrev_b32_e32 v6, 16, v52
	v_and_b32_e32 v7, 0xffff0000, v52
	v_lshlrev_b32_e32 v8, 16, v53
	v_and_b32_e32 v9, 0xffff0000, v53
	v_lshlrev_b32_e32 v10, 16, v54
	v_and_b32_e32 v11, 0xffff0000, v54
	v_lshlrev_b32_e32 v12, 16, v55
	v_and_b32_e32 v13, 0xffff0000, v55
	v_lshlrev_b32_e32 v14, 16, v56
	v_and_b32_e32 v15, 0xffff0000, v56
	v_lshlrev_b32_e32 v100, 16, v57
	v_and_b32_e32 v101, 0xffff0000, v57
	v_lshlrev_b32_e32 v102, 16, v58
	v_and_b32_e32 v103, 0xffff0000, v58
	v_lshlrev_b32_e32 v104, 16, v59
	v_and_b32_e32 v105, 0xffff0000, v59
	v_lshlrev_b32_e32 v106, 16, v60
	v_and_b32_e32 v107, 0xffff0000, v60
	v_lshlrev_b32_e32 v108, 16, v61
	v_and_b32_e32 v109, 0xffff0000, v61
	s_waitcnt vmcnt(6)
	v_lshlrev_b32_e32 v110, 16, v62
	v_and_b32_e32 v111, 0xffff0000, v62
	v_lshlrev_b32_e32 v112, 16, v63
	v_and_b32_e32 v113, 0xffff0000, v63
	v_lshlrev_b32_e32 v114, 16, v64
	v_and_b32_e32 v115, 0xffff0000, v64
	v_lshlrev_b32_e32 v116, 16, v65
	v_and_b32_e32 v117, 0xffff0000, v65
	v_pk_mul_f32 v[124:125], v[16:17], v[2:3]
	v_pk_mul_f32 v[126:127], v[18:19], v[4:5]
	v_pk_mul_f32 v[118:119], v[20:21], v[6:7]
	v_pk_mul_f32 v[120:121], v[22:23], v[8:9]
	v_pk_fma_f32 v[124:125], v[24:25], v[10:11], v[124:125]
	v_pk_fma_f32 v[126:127], v[26:27], v[12:13], v[126:127]
	v_pk_fma_f32 v[118:119], v[30:31], v[14:15], v[118:119]
	v_pk_fma_f32 v[120:121], v[32:33], v[100:101], v[120:121]
	v_pk_fma_f32 v[124:125], v[34:35], v[102:103], v[124:125]
	v_pk_fma_f32 v[126:127], v[36:37], v[104:105], v[126:127]
	v_pk_fma_f32 v[118:119], v[38:39], v[106:107], v[118:119]
	v_pk_fma_f32 v[120:121], v[40:41], v[108:109], v[120:121]
	v_pk_fma_f32 v[124:125], v[42:43], v[110:111], v[124:125]
	v_pk_fma_f32 v[126:127], v[44:45], v[112:113], v[126:127]
	v_pk_fma_f32 v[118:119], v[46:47], v[114:115], v[118:119]
	v_pk_fma_f32 v[120:121], v[48:49], v[116:117], v[120:121]
	v_mul_f32_e32 v2, 0xbfb8aa3b, v124
	v_mul_f32_e32 v3, 0xbfb8aa3b, v125
	v_mul_f32_e32 v4, 0xbfb8aa3b, v126
	v_mul_f32_e32 v5, 0xbfb8aa3b, v127
	v_mul_f32_e32 v6, 0xbfb8aa3b, v118
	v_mul_f32_e32 v7, 0xbfb8aa3b, v119
	v_mul_f32_e32 v8, 0xbfb8aa3b, v120
	v_mul_f32_e32 v9, 0xbfb8aa3b, v121
	v_exp_f32_e32 v2, v2
	v_exp_f32_e32 v3, v3
	v_exp_f32_e32 v4, v4
	v_exp_f32_e32 v5, v5
	v_exp_f32_e32 v6, v6
	v_exp_f32_e32 v7, v7
	v_exp_f32_e32 v8, v8
	v_exp_f32_e32 v9, v9
	v_add_f32_e32 v2, 1.0, v2
	v_add_f32_e32 v3, 1.0, v3
	v_add_f32_e32 v4, 1.0, v4
	v_add_f32_e32 v5, 1.0, v5
	v_add_f32_e32 v6, 1.0, v6
	v_add_f32_e32 v7, 1.0, v7
	v_add_f32_e32 v8, 1.0, v8
	v_add_f32_e32 v9, 1.0, v9
	v_rcp_f32_e32 v2, v2
	v_rcp_f32_e32 v3, v3
	v_rcp_f32_e32 v4, v4
	v_rcp_f32_e32 v5, v5
	v_rcp_f32_e32 v6, v6
	v_rcp_f32_e32 v7, v7
	v_rcp_f32_e32 v8, v8
	v_rcp_f32_e32 v9, v9
	v_pk_mul_f32 v[124:125], v[124:125], v[2:3]
	v_pk_mul_f32 v[126:127], v[126:127], v[4:5]
	v_pk_mul_f32 v[118:119], v[118:119], v[6:7]
	v_pk_mul_f32 v[120:121], v[120:121], v[8:9]
	ds_write_b128 v178, v[124:127] offset:0
	ds_write_b128 v178, v[118:121] offset:16
